# per-panel seams 2/3 + L2-shared granule exchange, now guarded by a run-time XCC co-location check (each WG publishes its XCC id; placement-independent fallback paths otherwise)
# baseline (speedup 1.0000x reference)
; #define LAS __attribute__((address_space(3)))
; __device__ __forceinline__ unsigned xb_add(unsigned* p, unsigned v) { return __hip_atomic_fetch_add(p, v, __ATOMIC_RELAXED, __HIP_MEMORY_SCOPE_AGENT); }
; __device__ __forceinline__ unsigned xb_xcc_id() { return (unsigned)__builtin_amdgcn_s_getreg((3 << 11) | 20) & 0xFu; }
; __device__ __forceinline__ XcdBarrier xcd_barrier_post(unsigned* bar, volatile LAS unsigned* st, unsigned G) {
;     XcdBarrier b; b.bar = bar; b.x = xb_xcc_id(); b.st = st; b.G = G; b.w0 = (__builtin_amdgcn_readfirstlane((int)(threadIdx.x >> 6)) == 0) ? 1 : 0;
;     if (threadIdx.x == 0) (void)xb_add(&bar[XB_XCNT(b.x)], 1u);
;     return b;
.LBB0_14:
	s_or_b64 exec, exec, s[2:3]
	s_load_dwordx16 s[36:51], s[0:1], 0x0
	s_load_dwordx16 s[8:23], s[0:1], 0x40
	s_lshl_b32 s0, s33, 2
	s_add_u32 s0, s34, s0
	s_addc_u32 s1, s35, 0
	s_add_u32 s52, s0, 0x14000
	s_getreg_b32 s0, hwreg(HW_REG_XCC_ID, 0, 4)
	s_addc_u32 s53, s1, 0
	s_and_b32 s0, s0, 15
	s_mov_b32 s67, 0
	v_writelane_b32 v254, s0, 5
	v_readfirstlane_b32 s0, v0
	s_nop 1
	v_writelane_b32 v254, s0, 6
	s_and_saveexec_b64 s[0:1], vcc
	s_cbranch_execz .LBB0_17
	s_mov_b64 s[2:3], exec
	v_mbcnt_lo_u32_b32 v0, s2, 0
	v_mbcnt_hi_u32_b32 v0, s3, v0
	v_cmp_eq_u32_e32 vcc, 0, v0
	s_and_b64 s[4:5], exec, vcc
	s_mov_b64 exec, s[4:5]
	s_cbranch_execz .LBB0_17
	v_readlane_b32 s4, v254, 5
	s_lshl_b32 s4, s4, 8
	s_bcnt1_i32_b64 s2, s[2:3]
	v_mov_b32_e32 v0, s4
	v_mov_b32_e32 v1, s2
	global_atomic_add v0, v1, s[52:53] offset:1024
	s_add_u32 s100, s34, 0x1c800
	s_addc_u32 s101, s35, 0
	s_lshl_b32 s99, s54, 2
	v_mov_b32_e32 v0, s99
	v_readlane_b32 s99, v254, 5
	s_add_i32 s99, s99, 1
	v_mov_b32_e32 v1, s99
	global_store_dword v0, v1, s[100:101] sc1

; __device__ __forceinline__ int lane_id() { int l; asm volatile("v_mbcnt_lo_u32_b32 %0, -1, 0\n\tv_mbcnt_hi_u32_b32 %0, -1, %0" : "=v"(l)); return l; }
; __device__ __forceinline__ void xcd_barrier(const XcdBarrier& b) {
;     asm volatile("s_waitcnt vmcnt(0)" ::: "memory");
;     __syncthreads();
;     if (b.w0 != 0 && lane_id() == 0) {
;         unsigned* bar = b.bar;
;         __builtin_amdgcn_s_waitcnt(0);
;         unsigned nloc = b.st[0], nx = b.st[1];
;         if (nloc == 0u) { xcd_barrier_complete(bar, b.x, b.G, nloc, nx); b.st[0] = nloc; b.st[1] = nx; }
.LBB0_99:
	v_mbcnt_lo_u32_b32 v0, -1, 0
	v_mbcnt_hi_u32_b32 v0, -1, v0
	v_readlane_b32 s99, v254, 25
	s_and_b32 s99, s99, 0xffffffc7
	v_lshlrev_b32_e32 v0, 3, v0
	v_and_b32_e32 v0, 56, v0
	v_or_b32_e32 v0, s99, v0
	v_lshlrev_b32_e32 v0, 2, v0
	s_add_u32 s100, s34, 0x1c800
	s_addc_u32 s101, s35, 0
	global_load_dword v0, v0, s[100:101] sc1
	s_waitcnt vmcnt(0)
	v_readlane_b32 s99, v254, 5
	s_add_i32 s99, s99, 1
	v_cmp_ne_u32_e32 vcc, s99, v0
	s_cmp_lg_u64 vcc, 0
	s_cselect_b32 s98, 1, 0
	v_readlane_b32 s0, v254, 4
	s_cmp_gt_u32 s0, 63
	v_readlane_b32 s83, v254, 25
	v_readlane_b32 s84, v254, 8
	v_readlane_b32 s86, v254, 7
	s_barrier
	s_cbranch_scc1 .LBB0_153
	v_mbcnt_lo_u32_b32 v0, -1, 0
	v_mbcnt_hi_u32_b32 v0, -1, v0
	s_nop 0
	v_cmp_eq_u32_e32 vcc, 0, v0
	s_and_saveexec_b64 s[0:1], vcc
	s_cbranch_execz .LBB0_152
	s_add_i32 s2, 0, 0x20168
	v_mov_b32_e32 v0, s2
	s_waitcnt vmcnt(0) expcnt(0) lgkmcnt(0)
	ds_read_b32 v2, v0
	s_add_i32 s2, 0, 0x2016c
	v_mov_b32_e32 v0, s2
	ds_read_b32 v0, v0
	s_waitcnt lgkmcnt(1)
	v_cmp_ne_u32_e32 vcc, 0, v2
	s_cbranch_vccnz .LBB0_116
	s_add_u32 s2, s34, 0xae00
	s_addc_u32 s3, s35, 0
	s_add_u32 s4, s34, 0xb000
	s_addc_u32 s5, s35, 0
	s_add_u32 s6, s34, 0xb100
	s_addc_u32 s7, s35, 0
	s_add_u32 s8, s34, 0xb200
	s_addc_u32 s9, s35, 0
	s_add_u32 s10, s34, 0xb300
	s_addc_u32 s11, s35, 0
	s_add_u32 s12, s34, 0xb400
	s_addc_u32 s13, s35, 0
	s_add_u32 s14, s34, 0xb500
	s_addc_u32 s15, s35, 0
	s_add_u32 s16, s34, 0xb600
	s_addc_u32 s17, s35, 0
	s_add_u32 s20, s34, 0xb700
	s_addc_u32 s21, s35, 0
	s_add_u32 s24, s34, 0xb800
	s_addc_u32 s25, s35, 0
	s_add_u32 s36, s34, 0xb900
	s_addc_u32 s37, s35, 0
	s_add_u32 s40, s34, 0xba00
	s_addc_u32 s41, s35, 0
	s_add_u32 s42, s34, 0xbb00
	s_addc_u32 s43, s35, 0
	s_add_u32 s44, s34, 0xbc00
	s_addc_u32 s45, s35, 0
	s_add_u32 s46, s34, 0xbd00
	s_addc_u32 s47, s35, 0
	s_add_u32 s48, s34, 0xbe00
	s_addc_u32 s49, s35, 0
	s_add_u32 s50, s34, 0xbf00
	s_addc_u32 s51, s35, 0
	s_mov_b32 s66, 1
	v_mov_b32_e32 v16, 0
	s_movk_i32 s67, 0x100
	s_branch .LBB0_104

; __device__ __forceinline__ int lane_id() { int l; asm volatile("v_mbcnt_lo_u32_b32 %0, -1, 0\n\tv_mbcnt_hi_u32_b32 %0, -1, %0" : "=v"(l)); return l; }
; __device__ __forceinline__ unsigned xb_add(unsigned* p, unsigned v) { return __hip_atomic_fetch_add(p, v, __ATOMIC_RELAXED, __HIP_MEMORY_SCOPE_AGENT); }
; __device__ __forceinline__ void xcd_arrive(const XcdBarrier& b) {
;     asm volatile("s_waitcnt vmcnt(0)" ::: "memory");
;     __syncthreads();
;     if (b.w0 != 0 && lane_id() == 0) {
;         unsigned* bar = b.bar;
;         __builtin_amdgcn_s_waitcnt(0);
;         unsigned nloc = b.st[0], nx = b.st[1];
;         if (nloc == 0u) { xcd_barrier_complete(bar, b.x, b.G, nloc, nx); b.st[0] = nloc; b.st[1] = nx; }
;         const unsigned old = xb_add(&bar[XB_XSUB(b.x)], 1u);
;         const unsigned gen = old / nloc;
;         if (old + 1u == (gen + 1u) * nloc) {
;             __builtin_amdgcn_fence(__ATOMIC_RELEASE, "agent");
;             asm volatile("s_waitcnt vmcnt(0)" ::: "memory");
.LBB0_456:
	s_waitcnt vmcnt(0)
	s_barrier
	s_waitcnt vmcnt(0)
	s_and_b64 vcc, exec, s[94:95]
	s_barrier
	s_cbranch_vccnz .LBB0_482
	v_mbcnt_lo_u32_b32 v0, -1, 0
	v_mbcnt_hi_u32_b32 v0, -1, v0
	s_nop 0
	v_cmp_eq_u32_e32 vcc, 0, v0
	s_and_saveexec_b64 s[4:5], vcc
	s_cbranch_execz .LBB0_481
	s_cmp_eq_u32 s98, 0
	s_cbranch_scc1 .Lpa2_fast
	buffer_wbl2 sc1
	s_waitcnt vmcnt(0)
.Lpa2_fast:
	v_readlane_b32 s0, v254, 19
	v_readlane_b32 s1, v254, 21
	s_add_i32 s0, s0, s1
	s_lshl_b32 s0, s0, 7
	s_add_u32 s0, s0, 0x7000
	v_mov_b32_e32 v0, s0
	v_mov_b32_e32 v1, 1
	global_atomic_add v0, v1, s[52:53]

; __device__ __forceinline__ int lane_id() { int l; asm volatile("v_mbcnt_lo_u32_b32 %0, -1, 0\n\tv_mbcnt_hi_u32_b32 %0, -1, %0" : "=v"(l)); return l; }
; __device__ __forceinline__ unsigned xb_add(unsigned* p, unsigned v) { return __hip_atomic_fetch_add(p, v, __ATOMIC_RELAXED, __HIP_MEMORY_SCOPE_AGENT); }
; __device__ __forceinline__ void xcd_arrive(const XcdBarrier& b) {
;     asm volatile("s_waitcnt vmcnt(0)" ::: "memory");
;     __syncthreads();
;     if (b.w0 != 0 && lane_id() == 0) {
;         unsigned* bar = b.bar;
;         __builtin_amdgcn_s_waitcnt(0);
;         unsigned nloc = b.st[0], nx = b.st[1];
;         if (nloc == 0u) { xcd_barrier_complete(bar, b.x, b.G, nloc, nx); b.st[0] = nloc; b.st[1] = nx; }
;         const unsigned old = xb_add(&bar[XB_XSUB(b.x)], 1u);
;         const unsigned gen = old / nloc;
;         if (old + 1u == (gen + 1u) * nloc) {
;             __builtin_amdgcn_fence(__ATOMIC_RELEASE, "agent");
;             asm volatile("s_waitcnt vmcnt(0)" ::: "memory");
; template <int UPTO>
; __device__ __forceinline__ void program(Frame& F, const XcdBarrier& bar, const XcdBarrier& gbar, const XcdBarrier& sbar, const int half, const int xl, const int jx) {
;     ...
;         xcd_arrive(sbar);
.LBB0_528:
	s_waitcnt vmcnt(0)
	s_barrier
	s_waitcnt vmcnt(0)
	s_and_b64 vcc, exec, s[94:95]
	s_barrier
	s_cbranch_vccnz .LBB0_554
	v_mbcnt_lo_u32_b32 v0, -1, 0
	v_mbcnt_hi_u32_b32 v0, -1, v0
	s_nop 0
	v_cmp_eq_u32_e32 vcc, 0, v0
	s_and_saveexec_b64 s[6:7], vcc
	s_cbranch_execz .LBB0_553
	s_cmp_eq_u32 s98, 0
	s_cbranch_scc1 .Lpa3_fast
	buffer_wbl2 sc1
	s_waitcnt vmcnt(0)
.Lpa3_fast:
	v_readlane_b32 s0, v254, 19
	v_readlane_b32 s1, v254, 21
	s_add_i32 s0, s0, s1
	s_lshl_b32 s0, s0, 7
	s_add_u32 s0, s0, 0x7800
	v_mov_b32_e32 v0, s0
	v_mov_b32_e32 v1, 1
	global_atomic_add v0, v1, s[52:53]

;     __device__ __forceinline__ bool run(const f32x4 (&v)[2][2][4][2], const Unit& u, int wr, int wc, int fr, int fq, PG8_LAS unsigned char* lds, int wid, int lane) const {
;     ...
;         const int row = wid * 32 + (lane & 31);
;         if (lane < 32) { const float tot = (P[row * 4 + 0] + P[row * 4 + 1]) + (P[row * 4 + 2] + P[row * 4 + 3]);
;             __hip_atomic_store(xbuf + ((size_t)(u.pm * BM + row) * 8 + u.pn), __float_as_uint(tot), __ATOMIC_RELAXED, __HIP_MEMORY_SCOPE_AGENT); }
.LBB0_600:
	s_or_b64 exec, exec, s[0:1]
	s_waitcnt lgkmcnt(0)
	s_barrier
	s_waitcnt lgkmcnt(0)
	v_and_or_b32 v147, v249, 31, s65
	v_add_u32_e32 v144, s6, v147
	v_cmp_gt_u32_e64 s[0:1], 32, v146
	v_ashrrev_i32_e32 v145, 31, v144
	s_cmp_lg_u32 s98, 0
	s_cbranch_scc1 .Lgx_orig
	s_sub_u32 s6, s10, s34
	s_sub_u32 s6, s6, 0x2800000
	s_add_u32 s44, s10, s6
	s_addc_u32 s45, s11, 0
	s_add_u32 s44, s44, 0x100000
	s_addc_u32 s45, s45, 0
	s_sub_u32 s46, s22, s10
	s_lshl_b32 s46, s46, 1
	v_mov_b32_e32 v146, 0
	s_and_saveexec_b64 s[6:7], s[0:1]
	s_cbranch_execz .Lgx_end
	v_lshl_add_u32 v148, v147, 4, 0
	ds_read_b128 v[148:151], v148
	v_lshlrev_b32_e32 v159, 6, v144
	v_add_u32_e32 v160, s46, v159
	v_mov_b32_e32 v161, 0x13572468
	s_waitcnt lgkmcnt(0)
	v_mov_b32_e32 v154, v149
	v_mov_b32_e32 v155, v150
	v_mov_b32_e32 v149, v151
	v_pk_add_f32 v[148:149], v[154:155], v[148:149]
	s_nop 0
	v_pk_add_f32 v[148:149], v[148:149], v[148:149] op_sel:[0,1] op_sel_hi:[1,0]
	s_nop 0
	v_mov_b32_e32 v149, v161
	global_store_dwordx2 v160, v[148:149], s[44:45]
	s_movk_i32 s47, 0x4000

;     __device__ __forceinline__ bool run(const f32x4 (&v)[2][2][4][2], const Unit& u, int wr, int wc, int fr, int fq, PG8_LAS unsigned char* lds, int wid, int lane) const {
;     ...
;         const int row = wid * 32 + (lane & 31);
;         if (lane < 32) { const float tot = (P[row * 4 + 0] + P[row * 4 + 1]) + (P[row * 4 + 2] + P[row * 4 + 3]);
;             __hip_atomic_store(xbuf + ((size_t)(u.pm * BM + row) * 8 + u.pn), __float_as_uint(tot), __ATOMIC_RELAXED, __HIP_MEMORY_SCOPE_AGENT); }
.Lgx_end:
	s_or_b64 exec, exec, s[6:7]
	s_branch .Lgx_join
.Lgx_orig:
	s_and_saveexec_b64 s[6:7], s[0:1]
	s_cbranch_execz .LBB0_602
	v_lshl_add_u32 v148, v147, 4, 0
	ds_read_b128 v[148:151], v148
	v_lshlrev_b64 v[152:153], 5, v[144:145]
	s_waitcnt lgkmcnt(0)
	v_mov_b32_e32 v154, v149
	v_mov_b32_e32 v155, v150
	v_mov_b32_e32 v149, v151
	v_pk_add_f32 v[148:149], v[154:155], v[148:149]
	v_lshl_add_u64 v[150:151], s[22:23], 0, v[152:153]
	v_pk_add_f32 v[148:149], v[148:149], v[148:149] op_sel:[0,1] op_sel_hi:[1,0]
	global_store_dword v[150:151], v148, off sc1

;     __device__ __forceinline__ bool run(const f32x4 (&v)[2][2][4][2], const Unit& u, int wr, int wc, int fr, int fq, PG8_LAS unsigned char* lds, int wid, int lane) const {
;     ...
;         asm volatile("s_waitcnt lgkmcnt(0)" ::: "memory"); __builtin_amdgcn_s_barrier(); asm volatile("" ::: "memory");
;         return bad;
;     __device__ __forceinline__ void fused(f32x4 (&acc)[2][2][4][2], const Unit& u, int wr, int wc, int fr, int fq, PG8_LAS unsigned char* lds, int wid, int lane) const {
;     ...
;         const float qnan = __builtin_nanf("");
;         float rsv[2][4];
; #pragma unroll
;         for (int ai = 0; ai < 2; ++ai)
; #pragma unroll
;             for (int m = 0; m < 4; ++m) rsv[ai][m] = bad ? qnan : S[ai * HALF + wr * 64 + m * 16 + fr];
.Lgx_join:
	s_waitcnt lgkmcnt(0)
	s_barrier
	s_waitcnt lgkmcnt(0)
	v_cmp_ne_u32_e32 vcc, 0, v146
	v_cmp_eq_u32_e64 s[6:7], 0, v146
	v_lshl_add_u32 v145, v248, 2, s53
	v_mov_b32_e32 v156, 0x7fc00000
	v_mov_b32_e32 v158, 0x7fc00000
	s_cbranch_vccz .LBB0_629
	v_cndmask_b32_e64 v144, 0, 1, s[6:7]
	v_cmp_ne_u32_e64 s[0:1], 1, v144
	s_andn2_b64 vcc, exec, s[6:7]
	s_cbranch_vccz .LBB0_630

; __global__ void __launch_bounds__(NWAVES * 64, 2) mk_fwd(Args args) {
;     extern __shared__ __attribute__((aligned(16))) unsigned char lds[];
	.amdhsa_kernel _Z6mk_fwd4Args
		.amdhsa_group_segment_fixed_size 0
		.amdhsa_private_segment_fixed_size 0
		.amdhsa_kernarg_size 168
		.amdhsa_user_sgpr_count 2
		.amdhsa_user_sgpr_dispatch_ptr 0
		.amdhsa_user_sgpr_queue_ptr 0
		.amdhsa_user_sgpr_kernarg_segment_ptr 1
		.amdhsa_user_sgpr_dispatch_id 0
		.amdhsa_user_sgpr_kernarg_preload_length 0
		.amdhsa_user_sgpr_kernarg_preload_offset 0
		.amdhsa_user_sgpr_private_segment_size 0
		.amdhsa_uses_dynamic_stack 0
		.amdhsa_enable_private_segment 0
		.amdhsa_system_sgpr_workgroup_id_x 1
		.amdhsa_system_sgpr_workgroup_id_y 0
		.amdhsa_system_sgpr_workgroup_id_z 0
		.amdhsa_system_sgpr_workgroup_info 0
		.amdhsa_system_vgpr_workitem_id 0
		.amdhsa_next_free_vgpr 255
		.amdhsa_next_free_sgpr 102
		.amdhsa_accum_offset 256
		.amdhsa_reserve_vcc 1
		.amdhsa_float_round_mode_32 0
		.amdhsa_float_round_mode_16_64 0
		.amdhsa_float_denorm_mode_32 3
		.amdhsa_float_denorm_mode_16_64 3
		.amdhsa_dx10_clamp 1
		.amdhsa_ieee_mode 1
		.amdhsa_fp16_overflow 0
		.amdhsa_tg_split 0
		.amdhsa_exception_fp_ieee_invalid_op 0
		.amdhsa_exception_fp_denorm_src 0
		.amdhsa_exception_fp_ieee_div_zero 0
		.amdhsa_exception_fp_ieee_overflow 0
		.amdhsa_exception_fp_ieee_underflow 0
		.amdhsa_exception_fp_ieee_inexact 0
		.amdhsa_exception_int_div_zero 0
	.end_amdhsa_kernel

; __global__ void __launch_bounds__(NWAVES * 64, 2) mk_fwd(Args args) {
;     extern __shared__ __attribute__((aligned(16))) unsigned char lds[];
amdhsa.kernels:
  - .agpr_count:     0
    .args:
      - .offset:         0
        .size:           168
        .value_kind:     by_value
    .group_segment_fixed_size: 0
    .kernarg_segment_align: 8
    .kernarg_segment_size: 168
    .language:       OpenCL C
    .language_version:
      - 2
      - 0
    .max_flat_workgroup_size: 512
    .name:           _Z6mk_fwd4Args
    .private_segment_fixed_size: 0
    .sgpr_count:     108
    .sgpr_spill_count: 61
    .symbol:         _Z6mk_fwd4Args.kd
    .uniform_work_group_size: 1
    .uses_dynamic_stack: false
    .vgpr_count:     255
    .vgpr_spill_count: 0
    .wavefront_size: 64
